# attention P3: V kept row-major in LDS (6 ds_write_b128 instead of 48 ds_write_b16 scatter per thread) and PV operand fragments read with ds_read_b64_tr_b16
# baseline (speedup 1.0000x reference)
.LBB0_736:
	s_or_b64 exec, exec, s[6:7]
	s_waitcnt vmcnt(6)
	ds_write_b128 v177, v[48:51]
	v_lshrrev_b32_e32 v253, 3, v158
	v_mul_u32_u24_e32 v253, 0xc0, v253
	v_and_b32_e32 v254, 7, v158
	v_lshl_add_u32 v253, v254, 4, v253
	v_add_u32_e32 v253, 0xd800, v253
	ds_write_b128 v253, v[52:55]
	ds_write_b128 v179, v[56:59]
	ds_write_b128 v253, v[60:63] offset:12288
	s_waitcnt vmcnt(5)
	ds_write_b128 v181, v[64:67]
	s_waitcnt vmcnt(4)
	ds_write_b128 v253, v[68:71] offset:24576
	ds_write_b128 v183, v[92:95]
	ds_write_b128 v253, v[96:99] offset:36864
	ds_write_b128 v185, v[100:103]
	ds_write_b128 v253, v[104:107] offset:49152
	ds_write_b128 v187, v[108:111]
	ds_write_b128 v253, v[112:115] offset:61440
	v_mov_b32_e32 v0, s59
	s_waitcnt lgkmcnt(0)
	s_barrier
	ds_read_b32 v0, v0
	s_waitcnt vmcnt(0)
	v_mov_b64_e32 v[118:119], v[90:91]
	v_mov_b64_e32 v[122:123], v[86:87]
	v_mov_b64_e32 v[126:127], v[82:83]
	v_mov_b64_e32 v[130:131], v[78:79]
	s_waitcnt lgkmcnt(0)
	v_cmp_lt_i32_e64 s[4:5], s60, v0
	v_readfirstlane_b32 s89, v0
	s_and_b64 vcc, exec, s[4:5]
	v_mov_b64_e32 v[116:117], v[88:89]
	v_mov_b64_e32 v[120:121], v[84:85]
	v_mov_b64_e32 v[124:125], v[80:81]
	v_mov_b64_e32 v[128:129], v[76:77]
	s_cbranch_vccnz .LBB0_870
	s_and_b32 s15, s89, 7
	s_lshl_b32 s12, s15, 8
	s_and_b32 s20, s12, 0x100
	s_ashr_i32 s14, s89, 9
	s_add_i32 s17, s20, 0xffffff80
	s_bfe_u32 s13, s89, 0x20001
	s_mov_b64 s[10:11], -1
	s_mov_b64 s[6:7], 0
	s_cmp_lt_i32 s14, 1
	s_mov_b64 s[8:9], 0
	s_cbranch_scc1 .LBB0_743
	s_cmp_eq_u32 s14, 1
	s_mov_b64 s[8:9], -1
	s_cbranch_scc0 .LBB0_740
	v_or_b32_e32 v0, s17, v145
	s_cmp_lg_u32 s20, 0
	v_lshl_or_b32 v0, v0, 2, s13
	s_cselect_b64 vcc, -1, 0
	v_cndmask_b32_e32 v1, -1, v0, vcc
	s_mov_b64 s[8:9], 0

.LBB0_874:
	v_and_b32_e32 v3, 64, v189
	v_xor_b32_e32 v2, 32, v189
	v_add_u32_e32 v3, 64, v3
	v_add_u32_e32 v75, -1, v0
	v_lshlrev_b32_e32 v0, 5, v0
	v_cmp_lt_i32_e32 vcc, v2, v3
	v_add_u32_e32 v193, v1, v0
	v_bfe_u32 v254, v158, 5, 1
	v_bfe_u32 v255, v158, 2, 2
	v_lshl_add_u32 v254, v254, 2, v255
	v_mul_u32_u24_e32 v254, 0xc0, v254
	v_bfe_u32 v255, v158, 4, 1
	v_lshl_add_u32 v254, v255, 5, v254
	v_and_b32_e32 v255, 3, v158
	v_lshl_add_u32 v254, v255, 3, v254
	v_mul_u32_u24_e32 v255, 0xc0, v193
	v_add_u32_e32 v254, v254, v255
	v_add_u32_e32 v151, v175, v0
	v_cndmask_b32_e32 v2, v189, v2, vcc
	v_sub_u32_e32 v192, v176, v0
	v_add_u32_e32 v0, v193, v149
	v_mov_b32_e32 v35, 0
	v_lshlrev_b32_e32 v73, 2, v2
	v_mad_u64_u32 v[152:153], s[6:7], v0, s55, v[148:149]
	v_mov_b32_e32 v34, 0xff800000
	s_mov_b64 s[52:53], 0
	v_mov_b32_e32 v16, 0
	v_mov_b32_e32 v17, v35
	v_mov_b32_e32 v18, v35
	v_mov_b32_e32 v19, v35
	v_mov_b32_e32 v20, v35
	v_mov_b32_e32 v21, v35
	v_mov_b32_e32 v22, v35
	v_mov_b32_e32 v23, v35
	v_mov_b32_e32 v24, v35
	v_mov_b32_e32 v25, v35
	v_mov_b32_e32 v26, v35
	v_mov_b32_e32 v27, v35
	v_mov_b32_e32 v28, v35
	v_mov_b32_e32 v29, v35
	v_mov_b32_e32 v30, v35
	v_mov_b32_e32 v31, v35
	v_mov_b32_e32 v0, 0
	v_mov_b32_e32 v1, v35
	v_mov_b32_e32 v2, v35
	v_mov_b32_e32 v3, v35
	v_mov_b32_e32 v4, v35
	v_mov_b32_e32 v5, v35
	v_mov_b32_e32 v6, v35
	v_mov_b32_e32 v7, v35
	v_mov_b32_e32 v8, v35
	v_mov_b32_e32 v9, v35
	v_mov_b32_e32 v10, v35
	v_mov_b32_e32 v11, v35
	v_mov_b32_e32 v12, v35
	v_mov_b32_e32 v13, v35
	v_mov_b32_e32 v14, v35
	v_mov_b32_e32 v15, v35
.LBB0_875:
	v_mov_b32_e32 v153, v34
	v_mov_b32_e32 v194, v35
	ds_read_b128 v[32:35], v152
	ds_read_b128 v[140:143], v152 offset:32
	ds_read_b128 v[136:139], v152 offset:64
	ds_read_b128 v[132:135], v152 offset:96
	s_waitcnt lgkmcnt(3)
	v_mfma_f32_32x32x16_bf16 v[32:47], v[32:35], v[76:79], 0
	v_add_u32_e32 v195, 27, v192
	v_add_u32_e32 v196, v146, v151
	v_add_u32_e32 v197, 25, v192
	v_add_u32_e32 v198, 24, v192
	v_cmp_lt_u32_e32 vcc, s76, v196
	v_cmp_gt_u32_e64 s[36:37], s68, v195
	v_add_u32_e32 v199, 19, v192
	s_waitcnt lgkmcnt(2)
	v_mfma_f32_32x32x16_bf16 v[32:47], v[140:143], v[80:83], v[32:47]
	v_add_u32_e32 v200, 18, v192
	v_cmp_gt_u32_e64 s[6:7], s68, v197
	v_cmp_gt_u32_e64 s[8:9], s68, v198
	v_add_u32_e32 v201, 17, v192
	v_add_u32_e32 v202, 16, v192
	v_cmp_gt_u32_e64 s[10:11], s68, v199
	v_cmp_gt_u32_e64 s[12:13], s68, v200
	s_waitcnt lgkmcnt(1)
	v_mfma_f32_32x32x16_bf16 v[32:47], v[136:139], v[84:87], v[32:47]
	v_add_u32_e32 v203, 11, v192
	v_add_u32_e32 v204, 10, v192
	v_cmp_gt_u32_e64 s[14:15], s68, v201
	v_cmp_gt_u32_e64 s[16:17], s68, v202
	v_add_u32_e32 v205, 9, v192
	v_add_u32_e32 v206, 8, v192
	v_cmp_gt_u32_e64 s[18:19], s68, v203
	s_waitcnt lgkmcnt(0)
	v_mfma_f32_32x32x16_bf16 v[32:47], v[132:135], v[88:91], v[32:47]
	v_cmp_gt_u32_e64 s[20:21], s68, v204
	v_add_u32_e32 v207, 3, v192
	v_add_u32_e32 v208, 2, v192
	v_cmp_gt_u32_e64 s[22:23], s68, v205
	v_cmp_gt_u32_e64 s[24:25], s68, v206
	v_add_u32_e32 v209, 1, v192
	v_cmp_gt_u32_e64 s[26:27], s68, v207
	s_nop 4
	v_cndmask_b32_e64 v32, v190, v32, s[36:37]
	v_cndmask_b32_e32 v33, v190, v33, vcc
	v_cndmask_b32_e64 v132, v190, v34, s[6:7]
	v_cndmask_b32_e64 v35, v190, v35, s[8:9]
	v_max3_f32 v34, v32, s69, v33
	v_cndmask_b32_e64 v36, v190, v36, s[10:11]
	v_cndmask_b32_e64 v37, v190, v37, s[12:13]
	v_max3_f32 v34, v34, v132, v35
	v_cndmask_b32_e64 v38, v190, v38, s[14:15]
	v_cndmask_b32_e64 v39, v190, v39, s[16:17]
	v_max3_f32 v34, v34, v36, v37
	v_cndmask_b32_e64 v40, v190, v40, s[18:19]
	v_cndmask_b32_e64 v41, v190, v41, s[20:21]
	v_max3_f32 v34, v34, v38, v39
	v_cmp_gt_u32_e64 s[28:29], s68, v208
	v_cndmask_b32_e64 v42, v190, v42, s[22:23]
	v_cndmask_b32_e64 v43, v190, v43, s[24:25]
	v_max3_f32 v34, v34, v40, v41
	v_cmp_gt_u32_e64 s[30:31], s68, v209
	v_cmp_gt_u32_e64 s[34:35], s68, v192
	v_cndmask_b32_e64 v44, v190, v44, s[26:27]
	v_cndmask_b32_e64 v45, v190, v45, s[28:29]
	v_max3_f32 v34, v34, v42, v43
	v_cndmask_b32_e64 v46, v190, v46, s[30:31]
	v_cndmask_b32_e64 v47, v190, v47, s[34:35]
	v_max3_f32 v34, v34, v44, v45
	v_max3_f32 v34, v34, v46, v47
	ds_bpermute_b32 v133, v73, v34
	v_add_u32_e32 v210, v146, v193
	v_add_u32_e32 v211, 8, v210
	v_add_u32_e32 v212, 16, v210
	v_add_u32_e32 v213, 24, v210
	s_waitcnt lgkmcnt(0)
	v_max3_f32 v34, v153, v34, v133
	v_sub_f32_e32 v32, v32, v34
	v_sub_f32_e32 v133, v153, v34
	v_sub_f32_e32 v33, v33, v34
	v_mul_f32_e32 v32, 0x3fb8aa3b, v32
	v_sub_f32_e32 v132, v132, v34
	v_mul_f32_e32 v133, 0x3fb8aa3b, v133
	v_mul_f32_e32 v33, 0x3fb8aa3b, v33
	v_exp_f32_e32 v134, v32
	v_sub_f32_e32 v35, v35, v34
	v_mul_f32_e32 v132, 0x3fb8aa3b, v132
	v_exp_f32_e32 v33, v33
	v_exp_f32_e32 v32, v133
	v_sub_f32_e32 v36, v36, v34
	v_mul_f32_e32 v35, 0x3fb8aa3b, v35
	v_exp_f32_e32 v153, v132
	v_sub_f32_e32 v37, v37, v34
	v_mul_f32_e32 v36, 0x3fb8aa3b, v36
	v_exp_f32_e32 v35, v35
	v_xor_b32_e32 v214, v210, v172
	v_xor_b32_e32 v141, v211, v172
	v_xor_b32_e32 v142, v212, v172
	v_xor_b32_e32 v143, v213, v172
	v_sub_f32_e32 v38, v38, v34
	v_sub_f32_e32 v39, v39, v34
	v_sub_f32_e32 v40, v40, v34
	v_sub_f32_e32 v41, v41, v34
	v_sub_f32_e32 v42, v42, v34
	v_sub_f32_e32 v43, v43, v34
	v_sub_f32_e32 v44, v44, v34
	v_sub_f32_e32 v45, v45, v34
	v_sub_f32_e32 v46, v46, v34
	v_sub_f32_e32 v47, v47, v34
	v_mul_f32_e32 v37, 0x3fb8aa3b, v37
	v_exp_f32_e32 v195, v36
	v_add_f32_e32 v207, 0, v134
	v_xor_b32_e32 v210, v210, v174
	v_lshl_add_u32 v140, v214, 1, v171
	v_xor_b32_e32 v211, v211, v174
	v_xor_b32_e32 v136, v213, v174
	v_lshl_add_u32 v137, v141, 1, v171
	v_lshl_add_u32 v138, v142, 1, v171
	v_lshl_add_u32 v139, v143, 1, v171
	v_mul_f32_e32 v38, 0x3fb8aa3b, v38
	v_mul_f32_e32 v39, 0x3fb8aa3b, v39
	v_mul_f32_e32 v40, 0x3fb8aa3b, v40
	v_mul_f32_e32 v41, 0x3fb8aa3b, v41
	v_mul_f32_e32 v42, 0x3fb8aa3b, v42
	v_mul_f32_e32 v43, 0x3fb8aa3b, v43
	v_mul_f32_e32 v44, 0x3fb8aa3b, v44
	v_mul_f32_e32 v45, 0x3fb8aa3b, v45
	v_mul_f32_e32 v46, 0x3fb8aa3b, v46
	v_mul_f32_e32 v47, 0x3fb8aa3b, v47
	v_exp_f32_e32 v196, v37
	v_pk_mul_f32 v[16:17], v[16:17], v[32:33] op_sel_hi:[1,0]
	v_pk_mul_f32 v[0:1], v[0:1], v[32:33] op_sel_hi:[1,0]
	v_pk_mul_f32 v[18:19], v[18:19], v[32:33] op_sel_hi:[1,0]
	v_pk_mul_f32 v[2:3], v[2:3], v[32:33] op_sel_hi:[1,0]
	v_pk_mul_f32 v[20:21], v[20:21], v[32:33] op_sel_hi:[1,0]
	v_pk_mul_f32 v[4:5], v[4:5], v[32:33] op_sel_hi:[1,0]
	v_pk_mul_f32 v[22:23], v[22:23], v[32:33] op_sel_hi:[1,0]
	v_pk_mul_f32 v[6:7], v[6:7], v[32:33] op_sel_hi:[1,0]
	v_cvt_pk_bf16_f32 v36, v134, v33
	v_pk_mul_f32 v[24:25], v[24:25], v[32:33] op_sel_hi:[1,0]
	v_pk_mul_f32 v[26:27], v[26:27], v[32:33] op_sel_hi:[1,0]
	v_pk_mul_f32 v[28:29], v[28:29], v[32:33] op_sel_hi:[1,0]
	v_pk_mul_f32 v[30:31], v[30:31], v[32:33] op_sel_hi:[1,0]
	v_pk_mul_f32 v[8:9], v[8:9], v[32:33] op_sel_hi:[1,0]
	v_pk_mul_f32 v[10:11], v[10:11], v[32:33] op_sel_hi:[1,0]
	v_pk_mul_f32 v[12:13], v[12:13], v[32:33] op_sel_hi:[1,0]
	v_pk_mul_f32 v[14:15], v[14:15], v[32:33] op_sel_hi:[1,0]
	v_add_f32_e32 v33, v33, v207
	v_lshl_add_u32 v210, v210, 1, v173
	v_lshl_add_u32 v141, v211, 1, v173
	v_lshl_add_u32 v143, v136, 1, v173
	v_exp_f32_e32 v197, v38
	v_exp_f32_e32 v198, v39
	v_exp_f32_e32 v199, v40
	v_exp_f32_e32 v200, v41
	v_exp_f32_e32 v201, v42
	v_exp_f32_e32 v202, v43
	v_exp_f32_e32 v203, v44
	v_exp_f32_e32 v204, v45
	v_exp_f32_e32 v205, v46
	v_exp_f32_e32 v206, v47
	v_cvt_pk_bf16_f32 v37, v153, v35
	v_cvt_pk_bf16_f32 v38, v195, v196
	v_cvt_pk_bf16_f32 v39, v197, v198
	v_cvt_pk_bf16_f32 v40, v199, v200
	v_cvt_pk_bf16_f32 v41, v201, v202
	v_cvt_pk_bf16_f32 v42, v203, v204
	v_cvt_pk_bf16_f32 v43, v205, v206
	ds_read_b64_tr_b16 v[44:45], v254 offset:55296
	ds_read_b64_tr_b16 v[46:47], v254 offset:56832
	ds_read_b64_tr_b16 v[132:133], v254 offset:58368
	ds_read_b64_tr_b16 v[134:135], v254 offset:59904
	ds_read_b64_tr_b16 v[136:137], v254 offset:55360
	ds_read_b64_tr_b16 v[138:139], v254 offset:56896
	v_add_f32_e32 v33, v153, v33
	v_add_f32_e32 v33, v35, v33
	v_add_f32_e32 v33, v195, v33
	v_add_f32_e32 v33, v196, v33
	v_add_f32_e32 v33, v197, v33
	s_waitcnt lgkmcnt(4)
	v_mfma_f32_32x32x16_bf16 v[16:31], v[44:47], v[36:39], v[16:31]
	v_add_f32_e32 v33, v198, v33
	v_xor_b32_e32 v212, v212, v174
	v_add_f32_e32 v33, v199, v33
	v_lshl_add_u32 v142, v212, 1, v173
	v_add_f32_e32 v33, v200, v33
	ds_read_b64_tr_b16 v[44:45], v254 offset:58432
	ds_read_b64_tr_b16 v[46:47], v254 offset:59968
	v_add_f32_e32 v33, v201, v33
	s_waitcnt lgkmcnt(2)
	v_mfma_f32_32x32x16_bf16 v[0:15], v[136:139], v[36:39], v[0:15]
	v_add_f32_e32 v33, v202, v33
	v_add_f32_e32 v33, v203, v33
	v_add_f32_e32 v33, v204, v33
	v_add_f32_e32 v33, v205, v33
	v_add_f32_e32 v33, v206, v33
	ds_bpermute_b32 v35, v73, v33
	v_add_u32_e32 v75, 1, v75
	v_mfma_f32_32x32x16_bf16 v[16:31], v[132:135], v[40:43], v[16:31]
	v_cmp_lt_i32_e32 vcc, 3, v75
	v_add_u32_e32 v151, 32, v151
	s_waitcnt lgkmcnt(0)
	v_add_f32_e32 v35, v33, v35
	v_add_u32_e32 v193, 32, v193
	v_add_u32_e32 v254, 0x1800, v254
	v_add_u32_e32 v152, 0x1200, v152
	s_or_b64 s[52:53], vcc, s[52:53]
	v_subrev_u32_e32 v192, 32, v192
	v_mfma_f32_32x32x16_bf16 v[0:15], v[44:47], v[40:43], v[0:15]
	v_fmac_f32_e32 v35, v194, v32
	s_andn2_b64 exec, exec, s[52:53]
	s_cbranch_execnz .LBB0_875
	s_or_b64 exec, exec, s[52:53]
	v_div_scale_f32 v32, s[6:7], v35, v35, 1.0
	v_rcp_f32_e32 v33, v32
	s_lshl_b32 s8, s51, 4
	s_and_b32 s9, s8, 0x1800
	s_bfe_u32 s8, s51, 0x40003
	v_fma_f32 v36, -v32, v33, 1.0
	v_fmac_f32_e32 v33, v36, v33
	v_div_scale_f32 v36, vcc, 1.0, v35, 1.0
	v_mul_f32_e32 v37, v36, v33
	v_fma_f32 v38, -v32, v37, v36
	v_fmac_f32_e32 v37, v38, v33
	s_ashr_i32 s51, s50, 31
	v_fma_f32 v32, -v32, v37, v36
	s_lshl_b64 s[6:7], s[50:51], 13
	v_mov_b32_e32 v75, v72
	v_div_fmas_f32 v32, v32, v33, v37
	s_or_b32 s6, s6, s9
	v_div_fixup_f32 v40, v32, v35, 1.0
	v_lshl_add_u64 v[32:33], s[6:7], 0, v[74:75]
	v_lshlrev_b64 v[36:37], 11, v[32:33]
	v_lshl_add_u64 v[36:37], s[42:43], 0, v[36:37]
	s_lshl_b32 s46, s8, 7
	v_mul_f32_e32 v16, v16, v40
	v_mul_f32_e32 v17, v17, v40
	v_lshl_add_u64 v[36:37], v[36:37], 0, s[46:47]
	v_lshlrev_b32_e32 v38, 1, v146
	v_mov_b32_e32 v39, v72
	v_cvt_pk_bf16_f32 v16, v16, v17
	v_mul_f32_e32 v17, v18, v40
	v_lshl_add_u64 v[36:37], v[36:37], 0, v[38:39]
	v_mul_f32_e32 v18, v19, v40
	v_cvt_pk_bf16_f32 v17, v17, v18
	global_store_dwordx2 v[36:37], v[16:17], off
	v_mul_f32_e32 v16, v20, v40
	v_mul_f32_e32 v17, v21, v40
	v_cvt_pk_bf16_f32 v16, v16, v17
	v_mul_f32_e32 v17, v22, v40
	v_mul_f32_e32 v18, v23, v40
	v_cvt_pk_bf16_f32 v17, v17, v18
	global_store_dwordx2 v[36:37], v[16:17], off offset:16
	v_mul_f32_e32 v16, v24, v40
	v_mul_f32_e32 v17, v25, v40
	v_cvt_pk_bf16_f32 v16, v16, v17
	v_mul_f32_e32 v17, v26, v40
	v_mul_f32_e32 v18, v27, v40
	v_cvt_pk_bf16_f32 v17, v17, v18
	global_store_dwordx2 v[36:37], v[16:17], off offset:32
	v_mul_f32_e32 v16, v28, v40
	v_mul_f32_e32 v17, v29, v40
	v_cvt_pk_bf16_f32 v16, v16, v17
	v_mul_f32_e32 v17, v30, v40
	v_mul_f32_e32 v0, v0, v40
	v_mul_f32_e32 v1, v1, v40
	v_mul_f32_e32 v18, v31, v40
	v_cvt_pk_bf16_f32 v17, v17, v18
	global_store_dwordx2 v[36:37], v[16:17], off offset:48
	v_cvt_pk_bf16_f32 v0, v0, v1
	v_mul_f32_e32 v1, v2, v40
	v_mul_f32_e32 v2, v3, v40
	v_cvt_pk_bf16_f32 v1, v1, v2
	global_store_dwordx2 v[36:37], v[0:1], off offset:64
	v_mul_f32_e32 v0, v4, v40
	v_mul_f32_e32 v1, v5, v40
	v_cvt_pk_bf16_f32 v0, v0, v1
	v_mul_f32_e32 v1, v6, v40
	v_mul_f32_e32 v2, v7, v40
	v_cvt_pk_bf16_f32 v1, v1, v2
	global_store_dwordx2 v[36:37], v[0:1], off offset:80
	v_mul_f32_e32 v0, v8, v40
	v_mul_f32_e32 v1, v9, v40
	v_cvt_pk_bf16_f32 v0, v0, v1
	v_mul_f32_e32 v1, v10, v40
	v_mul_f32_e32 v2, v11, v40
	v_cvt_pk_bf16_f32 v1, v1, v2
	global_store_dwordx2 v[36:37], v[0:1], off offset:96
	v_mul_f32_e32 v0, v12, v40
	v_mul_f32_e32 v1, v13, v40
	v_cvt_pk_bf16_f32 v0, v0, v1
	v_mul_f32_e32 v1, v14, v40
	v_mul_f32_e32 v2, v15, v40
	v_cvt_pk_bf16_f32 v1, v1, v2
	global_store_dwordx2 v[36:37], v[0:1], off offset:112
	s_and_saveexec_b64 s[6:7], s[2:3]
	s_cbranch_execz .LBB0_727
	v_cmp_gt_f32_e32 vcc, s77, v35
	s_lshl_b32 s46, s8, 2
	s_nop 0
	v_cndmask_b32_e64 v0, 0, 32, vcc
	v_ldexp_f32 v0, v35, v0
	v_log_f32_e32 v0, v0
	v_cndmask_b32_e32 v1, 0, v191, vcc
	v_mul_f32_e32 v2, 0x3f317217, v0
	v_fma_f32 v2, v0, s78, -v2
	v_fmac_f32_e32 v2, 0x3377d1cf, v0
	v_fmac_f32_e32 v2, 0x3f317217, v0
	v_cmp_lt_f32_e64 vcc, |v0|, s79
	s_nop 1
	v_cndmask_b32_e32 v0, v0, v2, vcc
	v_sub_f32_e32 v0, v0, v1
	v_add_f32_e32 v2, v34, v0
	v_lshlrev_b64 v[0:1], 6, v[32:33]
	v_lshl_add_u64 v[0:1], s[44:45], 0, v[0:1]
	v_lshl_add_u64 v[0:1], v[0:1], 0, s[46:47]
	global_store_dword v[0:1], v2, off
	s_branch .LBB0_727
